# scan compute body: 19 of 32 hazard nops per chunk replaced by moving the DPP add behind independent instructions (740 -> 721 instructions per 32 steps)
# speedup vs baseline: 1.0099x; 1.0099x over previous
; #define LAS __attribute__((address_space(3)))
; #define RW_LD(X, s) do { X.d = *(const LAS f32x4*)(bs + (s) * 256); X.k = *(const LAS f32x4*)(bs + 8192 + (s) * 256); X.a = *(const LAS f32x4*)(bs + 16384 + (s) * 256); \
;                          X.p = *(const LAS f32x4*)(bs + 24576 + (s) * 256); X.r = *(const LAS f32x4*)(bs + 32768 + (s) * 256); X.v = *(const LAS float*)(bv + (s) * 64); } while (0)
; #define RW_STEP(X, s) do { float sa = fmaf(S[3], X.k[3], fmaf(S[2], X.k[2], fmaf(S[1], X.k[1], S[0] * X.k[0]))); const f32x4 T = S * X.d + X.v * X.p; sa = -red16(sa); \
;                            S = T + sa * X.a; float y = fmaf(S[3], X.r[3], fmaf(S[2], X.r[2], fmaf(S[1], X.r[1], S[0] * X.r[0]))); y = red16(y); \
;                            yk = fmaf(selv[(s) & 15], y, yk); } while (0)
; #define RW_YST(s) do { if ((s) == 15) { ob[(size_t)(rowbase + c * 32 + seg) * D + 512 + h * 64 + vrow] = f2bf(yk); yk = 0.f; } } while (0)
; __device__ __forceinline__ void rwkv_scan(const Params& p, LAS unsigned char* lds, int rowbase, int T, int h, int q4, const float* S0, float* Sout) {
;     ...
;         if (comp) {
;             const LAS unsigned char* bs = b + seg * 16; const LAS unsigned char* bv = b + 40960 + vloc * 4;
;     ...
;             RwStep xa, xb, xc; float yk = 0.f;
;     ...
;             RW_LD(xa, 0); RW_LD(xb, 1);
; #pragma unroll
;             for (int s = 0; s < 30; s += 3) {
;                 RW_LD(xc, s + 2); RW_STEP(xa, s); RW_YST(s);
;                 RW_LD(xa, s + 3); RW_STEP(xb, s + 1); RW_YST(s + 1);
;                 RW_LD(xb, s + 4); RW_STEP(xc, s + 2); RW_YST(s + 2);
;             }
.Lrw3_cloop:
	s_barrier
	ds_read_b128 v[76:79], v2 offset:0
	ds_read_b128 v[84:87], v2 offset:16384
	ds_read_b128 v[80:83], v2 offset:8192
	ds_read_b128 v[124:127], v2 offset:24576
	ds_read_b128 v[24:27], v3 offset:0
	ds_read_b128 v[88:91], v2 offset:256
	ds_read_b128 v[96:99], v2 offset:16640
	ds_read_b128 v[92:95], v2 offset:8448
	ds_read_b128 v[128:131], v2 offset:24832
	ds_read_b128 v[100:103], v2 offset:512
	ds_read_b128 v[108:111], v2 offset:16896
	ds_read_b128 v[104:107], v2 offset:8704
	ds_read_b128 v[132:135], v2 offset:25088
	s_waitcnt lgkmcnt(8)
	v_pk_mul_f32 v[72:73], v[12:13], v[76:77]
	v_pk_fma_f32 v[72:73], v[14:15], v[78:79], v[72:73]
	ds_read_b128 v[112:115], v2 offset:768
	v_add_f32_e32 v74, v72, v73
	ds_read_b128 v[120:123], v2 offset:17152
	ds_read_b128 v[116:119], v2 offset:8960
	v_add_f32_dpp v74, v74, v74 quad_perm:[1,0,3,2] row_mask:0xf bank_mask:0xf bound_ctrl:1
	ds_read_b128 v[136:139], v2 offset:25344
	v_pk_fma_f32 v[16:17], v[24:25], v[84:85], v[12:13] op_sel_hi:[0,1,1]
	v_add_f32_dpp v74, v74, v74 quad_perm:[2,3,0,1] row_mask:0xf bank_mask:0xf bound_ctrl:1
	v_pk_fma_f32 v[18:19], v[24:25], v[86:87], v[14:15] op_sel_hi:[0,1,1]
	s_nop 0
	v_add_f32_dpp v74, v74, v74 row_half_mirror row_mask:0xf bank_mask:0xf bound_ctrl:1
	s_nop 1
	v_add_f32_dpp v74, v74, v74 row_mirror row_mask:0xf bank_mask:0xf bound_ctrl:1
	v_pk_fma_f32 v[12:13], v[80:81], v[74:75], v[16:17] op_sel_hi:[1,0,1] neg_lo:[0,1,0] neg_hi:[0,1,0]
	v_pk_fma_f32 v[14:15], v[82:83], v[74:75], v[18:19] op_sel_hi:[1,0,1] neg_lo:[0,1,0] neg_hi:[0,1,0]
	s_waitcnt lgkmcnt(8)
	v_pk_mul_f32 v[72:73], v[12:13], v[88:89]
	v_pk_fma_f32 v[72:73], v[14:15], v[90:91], v[72:73]
	ds_read_b128 v[76:79], v2 offset:1024
	v_add_f32_e32 v74, v72, v73
	ds_read_b128 v[84:87], v2 offset:17408
	ds_read_b128 v[80:83], v2 offset:9216
	v_add_f32_dpp v74, v74, v74 quad_perm:[1,0,3,2] row_mask:0xf bank_mask:0xf bound_ctrl:1
	ds_read_b128 v[140:143], v2 offset:25600
	ds_read_b128 v[28:31], v3 offset:16
	v_add_f32_dpp v74, v74, v74 quad_perm:[2,3,0,1] row_mask:0xf bank_mask:0xf bound_ctrl:1
	v_pk_fma_f32 v[16:17], v[24:25], v[96:97], v[12:13] op_sel:[1,0,0] op_sel_hi:[1,1,1]
	v_pk_fma_f32 v[18:19], v[24:25], v[98:99], v[14:15] op_sel:[1,0,0] op_sel_hi:[1,1,1]
	v_add_f32_dpp v74, v74, v74 row_half_mirror row_mask:0xf bank_mask:0xf bound_ctrl:1
	v_pk_mul_f32 v[198:199], v[12:13], v[124:125]
	v_pk_fma_f32 v[198:199], v[14:15], v[126:127], v[198:199]
	v_add_f32_dpp v74, v74, v74 row_mirror row_mask:0xf bank_mask:0xf bound_ctrl:1
	v_add_f32_e32 v144, v198, v199
	v_pk_fma_f32 v[12:13], v[92:93], v[74:75], v[16:17] op_sel_hi:[1,0,1] neg_lo:[0,1,0] neg_hi:[0,1,0]
	v_pk_fma_f32 v[14:15], v[94:95], v[74:75], v[18:19] op_sel_hi:[1,0,1] neg_lo:[0,1,0] neg_hi:[0,1,0]
	s_waitcnt lgkmcnt(9)
	v_pk_mul_f32 v[72:73], v[12:13], v[100:101]
	v_pk_fma_f32 v[72:73], v[14:15], v[102:103], v[72:73]
	ds_read_b128 v[88:91], v2 offset:1280
	v_add_f32_e32 v74, v72, v73
	ds_read_b128 v[96:99], v2 offset:17664
	ds_read_b128 v[92:95], v2 offset:9472
	v_add_f32_dpp v74, v74, v74 quad_perm:[1,0,3,2] row_mask:0xf bank_mask:0xf bound_ctrl:1
	ds_read_b128 v[124:127], v2 offset:25856
	v_pk_fma_f32 v[16:17], v[26:27], v[108:109], v[12:13] op_sel_hi:[0,1,1]
	v_add_f32_dpp v74, v74, v74 quad_perm:[2,3,0,1] row_mask:0xf bank_mask:0xf bound_ctrl:1
	v_pk_fma_f32 v[18:19], v[26:27], v[110:111], v[14:15] op_sel_hi:[0,1,1]
	v_pk_mul_f32 v[198:199], v[12:13], v[128:129]
	v_add_f32_dpp v74, v74, v74 row_half_mirror row_mask:0xf bank_mask:0xf bound_ctrl:1
	v_pk_fma_f32 v[198:199], v[14:15], v[130:131], v[198:199]
	v_add_f32_e32 v145, v198, v199
	v_add_f32_dpp v74, v74, v74 row_mirror row_mask:0xf bank_mask:0xf bound_ctrl:1
	v_pk_fma_f32 v[12:13], v[104:105], v[74:75], v[16:17] op_sel_hi:[1,0,1] neg_lo:[0,1,0] neg_hi:[0,1,0]
	v_pk_fma_f32 v[14:15], v[106:107], v[74:75], v[18:19] op_sel_hi:[1,0,1] neg_lo:[0,1,0] neg_hi:[0,1,0]
	s_waitcnt lgkmcnt(9)
	v_pk_mul_f32 v[72:73], v[12:13], v[112:113]
	v_pk_fma_f32 v[72:73], v[14:15], v[114:115], v[72:73]
	ds_read_b128 v[100:103], v2 offset:1536
	v_add_f32_e32 v74, v72, v73
	ds_read_b128 v[108:111], v2 offset:17920
	ds_read_b128 v[104:107], v2 offset:9728
	v_add_f32_dpp v74, v74, v74 quad_perm:[1,0,3,2] row_mask:0xf bank_mask:0xf bound_ctrl:1
	ds_read_b128 v[128:131], v2 offset:26112
	v_pk_fma_f32 v[16:17], v[26:27], v[120:121], v[12:13] op_sel:[1,0,0] op_sel_hi:[1,1,1]
	v_add_f32_dpp v74, v74, v74 quad_perm:[2,3,0,1] row_mask:0xf bank_mask:0xf bound_ctrl:1
	v_pk_fma_f32 v[18:19], v[26:27], v[122:123], v[14:15] op_sel:[1,0,0] op_sel_hi:[1,1,1]
	v_pk_mul_f32 v[198:199], v[12:13], v[132:133]
	v_add_f32_dpp v74, v74, v74 row_half_mirror row_mask:0xf bank_mask:0xf bound_ctrl:1
	v_pk_fma_f32 v[198:199], v[14:15], v[134:135], v[198:199]
	v_add_f32_e32 v146, v198, v199
	v_add_f32_dpp v74, v74, v74 row_mirror row_mask:0xf bank_mask:0xf bound_ctrl:1
	v_pk_fma_f32 v[12:13], v[116:117], v[74:75], v[16:17] op_sel_hi:[1,0,1] neg_lo:[0,1,0] neg_hi:[0,1,0]
	v_pk_fma_f32 v[14:15], v[118:119], v[74:75], v[18:19] op_sel_hi:[1,0,1] neg_lo:[0,1,0] neg_hi:[0,1,0]
	s_waitcnt lgkmcnt(8)
; #define LAS __attribute__((address_space(3)))
; #define RW_LD(X, s) do { X.d = *(const LAS f32x4*)(bs + (s) * 256); X.k = *(const LAS f32x4*)(bs + 8192 + (s) * 256); X.a = *(const LAS f32x4*)(bs + 16384 + (s) * 256); \
;                          X.p = *(const LAS f32x4*)(bs + 24576 + (s) * 256); X.r = *(const LAS f32x4*)(bs + 32768 + (s) * 256); X.v = *(const LAS float*)(bv + (s) * 64); } while (0)
; #define RW_STEP(X, s) do { float sa = fmaf(S[3], X.k[3], fmaf(S[2], X.k[2], fmaf(S[1], X.k[1], S[0] * X.k[0]))); const f32x4 T = S * X.d + X.v * X.p; sa = -red16(sa); \
;                            S = T + sa * X.a; float y = fmaf(S[3], X.r[3], fmaf(S[2], X.r[2], fmaf(S[1], X.r[1], S[0] * X.r[0]))); y = red16(y); \
;                            yk = fmaf(selv[(s) & 15], y, yk); } while (0)
; #define RW_YST(s) do { if ((s) == 15) { ob[(size_t)(rowbase + c * 32 + seg) * D + 512 + h * 64 + vrow] = f2bf(yk); yk = 0.f; } } while (0)
; __device__ __forceinline__ void rwkv_scan(const Params& p, LAS unsigned char* lds, int rowbase, int T, int h, int q4, const float* S0, float* Sout) {
;     ...
;         if (comp) {
;             const LAS unsigned char* bs = b + seg * 16; const LAS unsigned char* bv = b + 40960 + vloc * 4;
;     ...
;             RwStep xa, xb, xc; float yk = 0.f;
;     ...
;             RW_LD(xa, 0); RW_LD(xb, 1);
; #pragma unroll
;             for (int s = 0; s < 30; s += 3) {
;                 RW_LD(xc, s + 2); RW_STEP(xa, s); RW_YST(s);
;                 RW_LD(xa, s + 3); RW_STEP(xb, s + 1); RW_YST(s + 1);
;                 RW_LD(xb, s + 4); RW_STEP(xc, s + 2); RW_YST(s + 2);
;             }
	v_pk_mul_f32 v[72:73], v[12:13], v[76:77]
	v_pk_fma_f32 v[72:73], v[14:15], v[78:79], v[72:73]
	ds_read_b128 v[112:115], v2 offset:1792
	v_add_f32_e32 v74, v72, v73
	ds_read_b128 v[120:123], v2 offset:18176
	ds_read_b128 v[116:119], v2 offset:9984
	v_add_f32_dpp v74, v74, v74 quad_perm:[1,0,3,2] row_mask:0xf bank_mask:0xf bound_ctrl:1
	ds_read_b128 v[132:135], v2 offset:26368
	v_pk_fma_f32 v[16:17], v[28:29], v[84:85], v[12:13] op_sel_hi:[0,1,1]
	v_add_f32_dpp v74, v74, v74 quad_perm:[2,3,0,1] row_mask:0xf bank_mask:0xf bound_ctrl:1
	v_pk_fma_f32 v[18:19], v[28:29], v[86:87], v[14:15] op_sel_hi:[0,1,1]
	v_pk_mul_f32 v[198:199], v[12:13], v[136:137]
	v_add_f32_dpp v74, v74, v74 row_half_mirror row_mask:0xf bank_mask:0xf bound_ctrl:1
	v_pk_fma_f32 v[198:199], v[14:15], v[138:139], v[198:199]
	v_add_f32_e32 v147, v198, v199
	v_add_f32_dpp v74, v74, v74 row_mirror row_mask:0xf bank_mask:0xf bound_ctrl:1
	v_pk_fma_f32 v[12:13], v[80:81], v[74:75], v[16:17] op_sel_hi:[1,0,1] neg_lo:[0,1,0] neg_hi:[0,1,0]
	v_pk_fma_f32 v[14:15], v[82:83], v[74:75], v[18:19] op_sel_hi:[1,0,1] neg_lo:[0,1,0] neg_hi:[0,1,0]
	s_waitcnt lgkmcnt(8)
	v_pk_mul_f32 v[72:73], v[12:13], v[88:89]
	v_pk_fma_f32 v[72:73], v[14:15], v[90:91], v[72:73]
	ds_read_b128 v[76:79], v2 offset:2048
	v_add_f32_e32 v74, v72, v73
	ds_read_b128 v[84:87], v2 offset:18432
	ds_read_b128 v[80:83], v2 offset:10240
	v_add_f32_dpp v74, v74, v74 quad_perm:[1,0,3,2] row_mask:0xf bank_mask:0xf bound_ctrl:1
	ds_read_b128 v[136:139], v2 offset:26624
	ds_read_b128 v[24:27], v3 offset:32
	v_add_f32_dpp v74, v74, v74 quad_perm:[2,3,0,1] row_mask:0xf bank_mask:0xf bound_ctrl:1
	v_pk_fma_f32 v[16:17], v[28:29], v[96:97], v[12:13] op_sel:[1,0,0] op_sel_hi:[1,1,1]
	v_pk_fma_f32 v[18:19], v[28:29], v[98:99], v[14:15] op_sel:[1,0,0] op_sel_hi:[1,1,1]
	v_add_f32_dpp v74, v74, v74 row_half_mirror row_mask:0xf bank_mask:0xf bound_ctrl:1
	v_pk_mul_f32 v[198:199], v[12:13], v[140:141]
	v_pk_fma_f32 v[198:199], v[14:15], v[142:143], v[198:199]
	v_add_f32_dpp v74, v74, v74 row_mirror row_mask:0xf bank_mask:0xf bound_ctrl:1
	v_add_f32_e32 v148, v198, v199
	v_pk_fma_f32 v[12:13], v[92:93], v[74:75], v[16:17] op_sel_hi:[1,0,1] neg_lo:[0,1,0] neg_hi:[0,1,0]
	v_pk_fma_f32 v[14:15], v[94:95], v[74:75], v[18:19] op_sel_hi:[1,0,1] neg_lo:[0,1,0] neg_hi:[0,1,0]
	s_waitcnt lgkmcnt(9)
	v_pk_mul_f32 v[72:73], v[12:13], v[100:101]
	v_pk_fma_f32 v[72:73], v[14:15], v[102:103], v[72:73]
	ds_read_b128 v[88:91], v2 offset:2304
	v_add_f32_e32 v74, v72, v73
	ds_read_b128 v[96:99], v2 offset:18688
	ds_read_b128 v[92:95], v2 offset:10496
	v_add_f32_dpp v74, v74, v74 quad_perm:[1,0,3,2] row_mask:0xf bank_mask:0xf bound_ctrl:1
	ds_read_b128 v[140:143], v2 offset:26880
	v_pk_fma_f32 v[16:17], v[30:31], v[108:109], v[12:13] op_sel_hi:[0,1,1]
	v_add_f32_dpp v74, v74, v74 quad_perm:[2,3,0,1] row_mask:0xf bank_mask:0xf bound_ctrl:1
	v_pk_fma_f32 v[18:19], v[30:31], v[110:111], v[14:15] op_sel_hi:[0,1,1]
	v_pk_mul_f32 v[198:199], v[12:13], v[124:125]
	v_add_f32_dpp v74, v74, v74 row_half_mirror row_mask:0xf bank_mask:0xf bound_ctrl:1
	v_pk_fma_f32 v[198:199], v[14:15], v[126:127], v[198:199]
	v_add_f32_e32 v149, v198, v199
	v_add_f32_dpp v74, v74, v74 row_mirror row_mask:0xf bank_mask:0xf bound_ctrl:1
	v_pk_fma_f32 v[12:13], v[104:105], v[74:75], v[16:17] op_sel_hi:[1,0,1] neg_lo:[0,1,0] neg_hi:[0,1,0]
	v_pk_fma_f32 v[14:15], v[106:107], v[74:75], v[18:19] op_sel_hi:[1,0,1] neg_lo:[0,1,0] neg_hi:[0,1,0]
	s_waitcnt lgkmcnt(9)
	v_pk_mul_f32 v[72:73], v[12:13], v[112:113]
	v_pk_fma_f32 v[72:73], v[14:15], v[114:115], v[72:73]
	ds_read_b128 v[100:103], v2 offset:2560
	v_add_f32_e32 v74, v72, v73
	ds_read_b128 v[108:111], v2 offset:18944
	ds_read_b128 v[104:107], v2 offset:10752
	v_add_f32_dpp v74, v74, v74 quad_perm:[1,0,3,2] row_mask:0xf bank_mask:0xf bound_ctrl:1
	ds_read_b128 v[124:127], v2 offset:27136
	v_pk_fma_f32 v[16:17], v[30:31], v[120:121], v[12:13] op_sel:[1,0,0] op_sel_hi:[1,1,1]
	v_add_f32_dpp v74, v74, v74 quad_perm:[2,3,0,1] row_mask:0xf bank_mask:0xf bound_ctrl:1
	v_pk_fma_f32 v[18:19], v[30:31], v[122:123], v[14:15] op_sel:[1,0,0] op_sel_hi:[1,1,1]
	v_pk_mul_f32 v[198:199], v[12:13], v[128:129]
	v_add_f32_dpp v74, v74, v74 row_half_mirror row_mask:0xf bank_mask:0xf bound_ctrl:1
	v_pk_fma_f32 v[198:199], v[14:15], v[130:131], v[198:199]
	v_add_f32_e32 v150, v198, v199
	v_add_f32_dpp v74, v74, v74 row_mirror row_mask:0xf bank_mask:0xf bound_ctrl:1
	v_pk_fma_f32 v[12:13], v[116:117], v[74:75], v[16:17] op_sel_hi:[1,0,1] neg_lo:[0,1,0] neg_hi:[0,1,0]
	v_pk_fma_f32 v[14:15], v[118:119], v[74:75], v[18:19] op_sel_hi:[1,0,1] neg_lo:[0,1,0] neg_hi:[0,1,0]
	s_waitcnt lgkmcnt(8)
	v_pk_mul_f32 v[72:73], v[12:13], v[76:77]
	v_pk_fma_f32 v[72:73], v[14:15], v[78:79], v[72:73]
	ds_read_b128 v[112:115], v2 offset:2816
	v_add_f32_e32 v74, v72, v73
	ds_read_b128 v[120:123], v2 offset:19200
	ds_read_b128 v[116:119], v2 offset:11008
	v_add_f32_dpp v74, v74, v74 quad_perm:[1,0,3,2] row_mask:0xf bank_mask:0xf bound_ctrl:1
	ds_read_b128 v[128:131], v2 offset:27392
	v_pk_fma_f32 v[16:17], v[24:25], v[84:85], v[12:13] op_sel_hi:[0,1,1]
	v_add_f32_dpp v74, v74, v74 quad_perm:[2,3,0,1] row_mask:0xf bank_mask:0xf bound_ctrl:1
	v_pk_fma_f32 v[18:19], v[24:25], v[86:87], v[14:15] op_sel_hi:[0,1,1]
	v_pk_mul_f32 v[198:199], v[12:13], v[132:133]
	v_add_f32_dpp v74, v74, v74 row_half_mirror row_mask:0xf bank_mask:0xf bound_ctrl:1
	v_pk_fma_f32 v[198:199], v[14:15], v[134:135], v[198:199]
	v_add_f32_e32 v151, v198, v199
	v_add_f32_dpp v74, v74, v74 row_mirror row_mask:0xf bank_mask:0xf bound_ctrl:1
	v_pk_fma_f32 v[12:13], v[80:81], v[74:75], v[16:17] op_sel_hi:[1,0,1] neg_lo:[0,1,0] neg_hi:[0,1,0]
	v_pk_fma_f32 v[14:15], v[82:83], v[74:75], v[18:19] op_sel_hi:[1,0,1] neg_lo:[0,1,0] neg_hi:[0,1,0]
	s_waitcnt lgkmcnt(8)
; #define LAS __attribute__((address_space(3)))
; #define RW_LD(X, s) do { X.d = *(const LAS f32x4*)(bs + (s) * 256); X.k = *(const LAS f32x4*)(bs + 8192 + (s) * 256); X.a = *(const LAS f32x4*)(bs + 16384 + (s) * 256); \
;                          X.p = *(const LAS f32x4*)(bs + 24576 + (s) * 256); X.r = *(const LAS f32x4*)(bs + 32768 + (s) * 256); X.v = *(const LAS float*)(bv + (s) * 64); } while (0)
; #define RW_STEP(X, s) do { float sa = fmaf(S[3], X.k[3], fmaf(S[2], X.k[2], fmaf(S[1], X.k[1], S[0] * X.k[0]))); const f32x4 T = S * X.d + X.v * X.p; sa = -red16(sa); \
;                            S = T + sa * X.a; float y = fmaf(S[3], X.r[3], fmaf(S[2], X.r[2], fmaf(S[1], X.r[1], S[0] * X.r[0]))); y = red16(y); \
;                            yk = fmaf(selv[(s) & 15], y, yk); } while (0)
; #define RW_YST(s) do { if ((s) == 15) { ob[(size_t)(rowbase + c * 32 + seg) * D + 512 + h * 64 + vrow] = f2bf(yk); yk = 0.f; } } while (0)
; __device__ __forceinline__ void rwkv_scan(const Params& p, LAS unsigned char* lds, int rowbase, int T, int h, int q4, const float* S0, float* Sout) {
;     ...
;         if (comp) {
;             const LAS unsigned char* bs = b + seg * 16; const LAS unsigned char* bv = b + 40960 + vloc * 4;
;     ...
;             RwStep xa, xb, xc; float yk = 0.f;
;     ...
;             RW_LD(xa, 0); RW_LD(xb, 1);
; #pragma unroll
;             for (int s = 0; s < 30; s += 3) {
;                 RW_LD(xc, s + 2); RW_STEP(xa, s); RW_YST(s);
;                 RW_LD(xa, s + 3); RW_STEP(xb, s + 1); RW_YST(s + 1);
;                 RW_LD(xb, s + 4); RW_STEP(xc, s + 2); RW_YST(s + 2);
;             }
	v_pk_mul_f32 v[72:73], v[12:13], v[88:89]
	v_pk_fma_f32 v[72:73], v[14:15], v[90:91], v[72:73]
	ds_read_b128 v[76:79], v2 offset:3072
	v_add_f32_e32 v74, v72, v73
	ds_read_b128 v[84:87], v2 offset:19456
	ds_read_b128 v[80:83], v2 offset:11264
	v_add_f32_dpp v74, v74, v74 quad_perm:[1,0,3,2] row_mask:0xf bank_mask:0xf bound_ctrl:1
	ds_read_b128 v[132:135], v2 offset:27648
	ds_read_b128 v[28:31], v3 offset:48
	v_add_f32_dpp v74, v74, v74 quad_perm:[2,3,0,1] row_mask:0xf bank_mask:0xf bound_ctrl:1
	v_pk_fma_f32 v[16:17], v[24:25], v[96:97], v[12:13] op_sel:[1,0,0] op_sel_hi:[1,1,1]
	v_pk_fma_f32 v[18:19], v[24:25], v[98:99], v[14:15] op_sel:[1,0,0] op_sel_hi:[1,1,1]
	v_add_f32_dpp v74, v74, v74 row_half_mirror row_mask:0xf bank_mask:0xf bound_ctrl:1
	v_pk_mul_f32 v[198:199], v[12:13], v[136:137]
	v_pk_fma_f32 v[198:199], v[14:15], v[138:139], v[198:199]
	v_add_f32_dpp v74, v74, v74 row_mirror row_mask:0xf bank_mask:0xf bound_ctrl:1
	v_add_f32_e32 v152, v198, v199
	v_pk_fma_f32 v[12:13], v[92:93], v[74:75], v[16:17] op_sel_hi:[1,0,1] neg_lo:[0,1,0] neg_hi:[0,1,0]
	v_pk_fma_f32 v[14:15], v[94:95], v[74:75], v[18:19] op_sel_hi:[1,0,1] neg_lo:[0,1,0] neg_hi:[0,1,0]
	v_add_f32_dpp v176, v144, v144 row_mirror row_mask:0xf bank_mask:0x3
	s_waitcnt lgkmcnt(9)
	v_pk_mul_f32 v[72:73], v[12:13], v[100:101]
	v_add_f32_dpp v176, v152, v152 row_mirror row_mask:0xf bank_mask:0xc
	v_pk_fma_f32 v[72:73], v[14:15], v[102:103], v[72:73]
	ds_read_b128 v[88:91], v2 offset:3328
	v_add_f32_e32 v74, v72, v73
	ds_read_b128 v[96:99], v2 offset:19712
	ds_read_b128 v[92:95], v2 offset:11520
	v_add_f32_dpp v74, v74, v74 quad_perm:[1,0,3,2] row_mask:0xf bank_mask:0xf bound_ctrl:1
	ds_read_b128 v[136:139], v2 offset:27904
	v_pk_fma_f32 v[16:17], v[26:27], v[108:109], v[12:13] op_sel_hi:[0,1,1]
	v_add_f32_dpp v74, v74, v74 quad_perm:[2,3,0,1] row_mask:0xf bank_mask:0xf bound_ctrl:1
	v_pk_fma_f32 v[18:19], v[26:27], v[110:111], v[14:15] op_sel_hi:[0,1,1]
	v_pk_mul_f32 v[198:199], v[12:13], v[140:141]
	v_add_f32_dpp v74, v74, v74 row_half_mirror row_mask:0xf bank_mask:0xf bound_ctrl:1
	v_pk_fma_f32 v[198:199], v[14:15], v[142:143], v[198:199]
	v_add_f32_e32 v153, v198, v199
	v_add_f32_dpp v74, v74, v74 row_mirror row_mask:0xf bank_mask:0xf bound_ctrl:1
	v_pk_fma_f32 v[12:13], v[104:105], v[74:75], v[16:17] op_sel_hi:[1,0,1] neg_lo:[0,1,0] neg_hi:[0,1,0]
	v_pk_fma_f32 v[14:15], v[106:107], v[74:75], v[18:19] op_sel_hi:[1,0,1] neg_lo:[0,1,0] neg_hi:[0,1,0]
	v_add_f32_dpp v177, v145, v145 row_mirror row_mask:0xf bank_mask:0x3
	s_waitcnt lgkmcnt(9)
	v_pk_mul_f32 v[72:73], v[12:13], v[112:113]
	v_add_f32_dpp v177, v153, v153 row_mirror row_mask:0xf bank_mask:0xc
	v_pk_fma_f32 v[72:73], v[14:15], v[114:115], v[72:73]
	ds_read_b128 v[100:103], v2 offset:3584
	v_add_f32_e32 v74, v72, v73
	ds_read_b128 v[108:111], v2 offset:19968
	ds_read_b128 v[104:107], v2 offset:11776
	v_add_f32_dpp v74, v74, v74 quad_perm:[1,0,3,2] row_mask:0xf bank_mask:0xf bound_ctrl:1
	ds_read_b128 v[140:143], v2 offset:28160
	v_pk_fma_f32 v[16:17], v[26:27], v[120:121], v[12:13] op_sel:[1,0,0] op_sel_hi:[1,1,1]
	v_add_f32_dpp v74, v74, v74 quad_perm:[2,3,0,1] row_mask:0xf bank_mask:0xf bound_ctrl:1
	v_pk_fma_f32 v[18:19], v[26:27], v[122:123], v[14:15] op_sel:[1,0,0] op_sel_hi:[1,1,1]
	v_pk_mul_f32 v[198:199], v[12:13], v[124:125]
	v_add_f32_dpp v74, v74, v74 row_half_mirror row_mask:0xf bank_mask:0xf bound_ctrl:1
	v_pk_fma_f32 v[198:199], v[14:15], v[126:127], v[198:199]
	v_add_f32_e32 v154, v198, v199
	v_add_f32_dpp v74, v74, v74 row_mirror row_mask:0xf bank_mask:0xf bound_ctrl:1
	v_pk_fma_f32 v[12:13], v[116:117], v[74:75], v[16:17] op_sel_hi:[1,0,1] neg_lo:[0,1,0] neg_hi:[0,1,0]
	v_pk_fma_f32 v[14:15], v[118:119], v[74:75], v[18:19] op_sel_hi:[1,0,1] neg_lo:[0,1,0] neg_hi:[0,1,0]
	v_add_f32_dpp v178, v146, v146 row_mirror row_mask:0xf bank_mask:0x3
	s_waitcnt lgkmcnt(8)
	v_pk_mul_f32 v[72:73], v[12:13], v[76:77]
	v_add_f32_dpp v178, v154, v154 row_mirror row_mask:0xf bank_mask:0xc
	v_pk_fma_f32 v[72:73], v[14:15], v[78:79], v[72:73]
	ds_read_b128 v[112:115], v2 offset:3840
	v_add_f32_e32 v74, v72, v73
	ds_read_b128 v[120:123], v2 offset:20224
	ds_read_b128 v[116:119], v2 offset:12032
	v_add_f32_dpp v74, v74, v74 quad_perm:[1,0,3,2] row_mask:0xf bank_mask:0xf bound_ctrl:1
	ds_read_b128 v[124:127], v2 offset:28416
	v_pk_fma_f32 v[16:17], v[28:29], v[84:85], v[12:13] op_sel_hi:[0,1,1]
	v_add_f32_dpp v74, v74, v74 quad_perm:[2,3,0,1] row_mask:0xf bank_mask:0xf bound_ctrl:1
	v_pk_fma_f32 v[18:19], v[28:29], v[86:87], v[14:15] op_sel_hi:[0,1,1]
	v_pk_mul_f32 v[198:199], v[12:13], v[128:129]
	v_add_f32_dpp v74, v74, v74 row_half_mirror row_mask:0xf bank_mask:0xf bound_ctrl:1
	v_pk_fma_f32 v[198:199], v[14:15], v[130:131], v[198:199]
	v_add_f32_e32 v155, v198, v199
	v_add_f32_dpp v74, v74, v74 row_mirror row_mask:0xf bank_mask:0xf bound_ctrl:1
	v_pk_fma_f32 v[12:13], v[80:81], v[74:75], v[16:17] op_sel_hi:[1,0,1] neg_lo:[0,1,0] neg_hi:[0,1,0]
	v_pk_fma_f32 v[14:15], v[82:83], v[74:75], v[18:19] op_sel_hi:[1,0,1] neg_lo:[0,1,0] neg_hi:[0,1,0]
	v_add_f32_dpp v179, v147, v147 row_mirror row_mask:0xf bank_mask:0x3
	s_waitcnt lgkmcnt(8)
; #define LAS __attribute__((address_space(3)))
; #define RW_LD(X, s) do { X.d = *(const LAS f32x4*)(bs + (s) * 256); X.k = *(const LAS f32x4*)(bs + 8192 + (s) * 256); X.a = *(const LAS f32x4*)(bs + 16384 + (s) * 256); \
;                          X.p = *(const LAS f32x4*)(bs + 24576 + (s) * 256); X.r = *(const LAS f32x4*)(bs + 32768 + (s) * 256); X.v = *(const LAS float*)(bv + (s) * 64); } while (0)
; #define RW_STEP(X, s) do { float sa = fmaf(S[3], X.k[3], fmaf(S[2], X.k[2], fmaf(S[1], X.k[1], S[0] * X.k[0]))); const f32x4 T = S * X.d + X.v * X.p; sa = -red16(sa); \
;                            S = T + sa * X.a; float y = fmaf(S[3], X.r[3], fmaf(S[2], X.r[2], fmaf(S[1], X.r[1], S[0] * X.r[0]))); y = red16(y); \
;                            yk = fmaf(selv[(s) & 15], y, yk); } while (0)
; #define RW_YST(s) do { if ((s) == 15) { ob[(size_t)(rowbase + c * 32 + seg) * D + 512 + h * 64 + vrow] = f2bf(yk); yk = 0.f; } } while (0)
; __device__ __forceinline__ void rwkv_scan(const Params& p, LAS unsigned char* lds, int rowbase, int T, int h, int q4, const float* S0, float* Sout) {
;     ...
;         if (comp) {
;             const LAS unsigned char* bs = b + seg * 16; const LAS unsigned char* bv = b + 40960 + vloc * 4;
;     ...
;             RwStep xa, xb, xc; float yk = 0.f;
;     ...
;             RW_LD(xa, 0); RW_LD(xb, 1);
; #pragma unroll
;             for (int s = 0; s < 30; s += 3) {
;                 RW_LD(xc, s + 2); RW_STEP(xa, s); RW_YST(s);
;                 RW_LD(xa, s + 3); RW_STEP(xb, s + 1); RW_YST(s + 1);
;                 RW_LD(xb, s + 4); RW_STEP(xc, s + 2); RW_YST(s + 2);
;             }
	v_pk_mul_f32 v[72:73], v[12:13], v[88:89]
	v_add_f32_dpp v179, v155, v155 row_mirror row_mask:0xf bank_mask:0xc
	v_pk_fma_f32 v[72:73], v[14:15], v[90:91], v[72:73]
	ds_read_b128 v[76:79], v2 offset:4096
	v_add_f32_e32 v74, v72, v73
	ds_read_b128 v[84:87], v2 offset:20480
	ds_read_b128 v[80:83], v2 offset:12288
	v_add_f32_dpp v74, v74, v74 quad_perm:[1,0,3,2] row_mask:0xf bank_mask:0xf bound_ctrl:1
	ds_read_b128 v[128:131], v2 offset:28672
	ds_read_b128 v[24:27], v3 offset:64
	v_add_f32_dpp v74, v74, v74 quad_perm:[2,3,0,1] row_mask:0xf bank_mask:0xf bound_ctrl:1
	v_pk_fma_f32 v[16:17], v[28:29], v[96:97], v[12:13] op_sel:[1,0,0] op_sel_hi:[1,1,1]
	v_pk_fma_f32 v[18:19], v[28:29], v[98:99], v[14:15] op_sel:[1,0,0] op_sel_hi:[1,1,1]
	v_add_f32_dpp v74, v74, v74 row_half_mirror row_mask:0xf bank_mask:0xf bound_ctrl:1
	v_pk_mul_f32 v[198:199], v[12:13], v[132:133]
	v_pk_fma_f32 v[198:199], v[14:15], v[134:135], v[198:199]
	v_add_f32_dpp v74, v74, v74 row_mirror row_mask:0xf bank_mask:0xf bound_ctrl:1
	v_add_f32_e32 v156, v198, v199
	v_pk_fma_f32 v[12:13], v[92:93], v[74:75], v[16:17] op_sel_hi:[1,0,1] neg_lo:[0,1,0] neg_hi:[0,1,0]
	v_pk_fma_f32 v[14:15], v[94:95], v[74:75], v[18:19] op_sel_hi:[1,0,1] neg_lo:[0,1,0] neg_hi:[0,1,0]
	v_add_f32_dpp v180, v148, v148 row_mirror row_mask:0xf bank_mask:0x3
	s_waitcnt lgkmcnt(9)
	v_pk_mul_f32 v[72:73], v[12:13], v[100:101]
	v_add_f32_dpp v180, v156, v156 row_mirror row_mask:0xf bank_mask:0xc
	v_pk_fma_f32 v[72:73], v[14:15], v[102:103], v[72:73]
	ds_read_b128 v[88:91], v2 offset:4352
	v_add_f32_e32 v74, v72, v73
	ds_read_b128 v[96:99], v2 offset:20736
	ds_read_b128 v[92:95], v2 offset:12544
	v_add_f32_dpp v74, v74, v74 quad_perm:[1,0,3,2] row_mask:0xf bank_mask:0xf bound_ctrl:1
	ds_read_b128 v[132:135], v2 offset:28928
	v_pk_fma_f32 v[16:17], v[30:31], v[108:109], v[12:13] op_sel_hi:[0,1,1]
	v_add_f32_dpp v74, v74, v74 quad_perm:[2,3,0,1] row_mask:0xf bank_mask:0xf bound_ctrl:1
	v_pk_fma_f32 v[18:19], v[30:31], v[110:111], v[14:15] op_sel_hi:[0,1,1]
	v_pk_mul_f32 v[198:199], v[12:13], v[136:137]
	v_add_f32_dpp v74, v74, v74 row_half_mirror row_mask:0xf bank_mask:0xf bound_ctrl:1
	v_pk_fma_f32 v[198:199], v[14:15], v[138:139], v[198:199]
	v_add_f32_e32 v157, v198, v199
	v_add_f32_dpp v74, v74, v74 row_mirror row_mask:0xf bank_mask:0xf bound_ctrl:1
	v_pk_fma_f32 v[12:13], v[104:105], v[74:75], v[16:17] op_sel_hi:[1,0,1] neg_lo:[0,1,0] neg_hi:[0,1,0]
	v_pk_fma_f32 v[14:15], v[106:107], v[74:75], v[18:19] op_sel_hi:[1,0,1] neg_lo:[0,1,0] neg_hi:[0,1,0]
	v_add_f32_dpp v184, v176, v176 row_half_mirror row_mask:0xf bank_mask:0x5
	s_waitcnt lgkmcnt(9)
	v_pk_mul_f32 v[72:73], v[12:13], v[112:113]
	v_add_f32_dpp v184, v180, v180 row_half_mirror row_mask:0xf bank_mask:0xa
	v_pk_fma_f32 v[72:73], v[14:15], v[114:115], v[72:73]
	ds_read_b128 v[100:103], v2 offset:4608
	v_add_f32_e32 v74, v72, v73
	ds_read_b128 v[108:111], v2 offset:20992
	ds_read_b128 v[104:107], v2 offset:12800
	v_add_f32_dpp v74, v74, v74 quad_perm:[1,0,3,2] row_mask:0xf bank_mask:0xf bound_ctrl:1
	ds_read_b128 v[136:139], v2 offset:29184
	v_pk_fma_f32 v[16:17], v[30:31], v[120:121], v[12:13] op_sel:[1,0,0] op_sel_hi:[1,1,1]
	v_add_f32_dpp v74, v74, v74 quad_perm:[2,3,0,1] row_mask:0xf bank_mask:0xf bound_ctrl:1
	v_pk_fma_f32 v[18:19], v[30:31], v[122:123], v[14:15] op_sel:[1,0,0] op_sel_hi:[1,1,1]
	v_pk_mul_f32 v[198:199], v[12:13], v[140:141]
	v_add_f32_dpp v74, v74, v74 row_half_mirror row_mask:0xf bank_mask:0xf bound_ctrl:1
	v_pk_fma_f32 v[198:199], v[14:15], v[142:143], v[198:199]
	v_add_f32_e32 v158, v198, v199
	v_add_f32_dpp v74, v74, v74 row_mirror row_mask:0xf bank_mask:0xf bound_ctrl:1
	v_pk_fma_f32 v[12:13], v[116:117], v[74:75], v[16:17] op_sel_hi:[1,0,1] neg_lo:[0,1,0] neg_hi:[0,1,0]
	v_pk_fma_f32 v[14:15], v[118:119], v[74:75], v[18:19] op_sel_hi:[1,0,1] neg_lo:[0,1,0] neg_hi:[0,1,0]
	v_add_f32_dpp v181, v149, v149 row_mirror row_mask:0xf bank_mask:0x3
	v_add_f32_dpp v185, v177, v177 row_half_mirror row_mask:0xf bank_mask:0x5
	s_waitcnt lgkmcnt(8)
	v_add_f32_dpp v181, v157, v157 row_mirror row_mask:0xf bank_mask:0xc
	v_pk_mul_f32 v[72:73], v[12:13], v[76:77]
	v_pk_fma_f32 v[72:73], v[14:15], v[78:79], v[72:73]
	ds_read_b128 v[112:115], v2 offset:4864
	v_add_f32_e32 v74, v72, v73
	ds_read_b128 v[120:123], v2 offset:21248
	ds_read_b128 v[116:119], v2 offset:13056
	v_add_f32_dpp v74, v74, v74 quad_perm:[1,0,3,2] row_mask:0xf bank_mask:0xf bound_ctrl:1
	ds_read_b128 v[140:143], v2 offset:29440
	v_pk_fma_f32 v[16:17], v[24:25], v[84:85], v[12:13] op_sel_hi:[0,1,1]
	v_add_f32_dpp v74, v74, v74 quad_perm:[2,3,0,1] row_mask:0xf bank_mask:0xf bound_ctrl:1
	v_pk_fma_f32 v[18:19], v[24:25], v[86:87], v[14:15] op_sel_hi:[0,1,1]
	v_pk_mul_f32 v[198:199], v[12:13], v[124:125]
	v_add_f32_dpp v74, v74, v74 row_half_mirror row_mask:0xf bank_mask:0xf bound_ctrl:1
	v_pk_fma_f32 v[198:199], v[14:15], v[126:127], v[198:199]
	v_add_f32_e32 v159, v198, v199
	v_add_f32_dpp v74, v74, v74 row_mirror row_mask:0xf bank_mask:0xf bound_ctrl:1
	v_pk_fma_f32 v[12:13], v[80:81], v[74:75], v[16:17] op_sel_hi:[1,0,1] neg_lo:[0,1,0] neg_hi:[0,1,0]
	v_pk_fma_f32 v[14:15], v[82:83], v[74:75], v[18:19] op_sel_hi:[1,0,1] neg_lo:[0,1,0] neg_hi:[0,1,0]
	v_add_f32_dpp v185, v181, v181 row_half_mirror row_mask:0xf bank_mask:0xa
	v_add_f32_dpp v182, v150, v150 row_mirror row_mask:0xf bank_mask:0x3
	s_waitcnt lgkmcnt(8)
; #define LAS __attribute__((address_space(3)))
; #define RW_LD(X, s) do { X.d = *(const LAS f32x4*)(bs + (s) * 256); X.k = *(const LAS f32x4*)(bs + 8192 + (s) * 256); X.a = *(const LAS f32x4*)(bs + 16384 + (s) * 256); \
;                          X.p = *(const LAS f32x4*)(bs + 24576 + (s) * 256); X.r = *(const LAS f32x4*)(bs + 32768 + (s) * 256); X.v = *(const LAS float*)(bv + (s) * 64); } while (0)
; #define RW_STEP(X, s) do { float sa = fmaf(S[3], X.k[3], fmaf(S[2], X.k[2], fmaf(S[1], X.k[1], S[0] * X.k[0]))); const f32x4 T = S * X.d + X.v * X.p; sa = -red16(sa); \
;                            S = T + sa * X.a; float y = fmaf(S[3], X.r[3], fmaf(S[2], X.r[2], fmaf(S[1], X.r[1], S[0] * X.r[0]))); y = red16(y); \
;                            yk = fmaf(selv[(s) & 15], y, yk); } while (0)
; #define RW_YST(s) do { if ((s) == 15) { ob[(size_t)(rowbase + c * 32 + seg) * D + 512 + h * 64 + vrow] = f2bf(yk); yk = 0.f; } } while (0)
; __device__ __forceinline__ void rwkv_scan(const Params& p, LAS unsigned char* lds, int rowbase, int T, int h, int q4, const float* S0, float* Sout) {
;     ...
;         if (comp) {
;             const LAS unsigned char* bs = b + seg * 16; const LAS unsigned char* bv = b + 40960 + vloc * 4;
;     ...
;             RwStep xa, xb, xc; float yk = 0.f;
;     ...
;             RW_LD(xa, 0); RW_LD(xb, 1);
; #pragma unroll
;             for (int s = 0; s < 30; s += 3) {
;                 RW_LD(xc, s + 2); RW_STEP(xa, s); RW_YST(s);
;                 RW_LD(xa, s + 3); RW_STEP(xb, s + 1); RW_YST(s + 1);
;                 RW_LD(xb, s + 4); RW_STEP(xc, s + 2); RW_YST(s + 2);
;             }
	v_pk_mul_f32 v[72:73], v[12:13], v[88:89]
	v_add_f32_dpp v182, v158, v158 row_mirror row_mask:0xf bank_mask:0xc
	v_pk_fma_f32 v[72:73], v[14:15], v[90:91], v[72:73]
	ds_read_b128 v[76:79], v2 offset:5120
	v_add_f32_e32 v74, v72, v73
	ds_read_b128 v[84:87], v2 offset:21504
	ds_read_b128 v[80:83], v2 offset:13312
	v_add_f32_dpp v74, v74, v74 quad_perm:[1,0,3,2] row_mask:0xf bank_mask:0xf bound_ctrl:1
	ds_read_b128 v[124:127], v2 offset:29696
	ds_read_b128 v[28:31], v3 offset:80
	v_add_f32_dpp v74, v74, v74 quad_perm:[2,3,0,1] row_mask:0xf bank_mask:0xf bound_ctrl:1
	v_pk_fma_f32 v[16:17], v[24:25], v[96:97], v[12:13] op_sel:[1,0,0] op_sel_hi:[1,1,1]
	v_pk_fma_f32 v[18:19], v[24:25], v[98:99], v[14:15] op_sel:[1,0,0] op_sel_hi:[1,1,1]
	v_add_f32_dpp v74, v74, v74 row_half_mirror row_mask:0xf bank_mask:0xf bound_ctrl:1
	v_pk_mul_f32 v[198:199], v[12:13], v[128:129]
	v_pk_fma_f32 v[198:199], v[14:15], v[130:131], v[198:199]
	v_add_f32_dpp v74, v74, v74 row_mirror row_mask:0xf bank_mask:0xf bound_ctrl:1
	v_add_f32_e32 v160, v198, v199
	v_pk_fma_f32 v[12:13], v[92:93], v[74:75], v[16:17] op_sel_hi:[1,0,1] neg_lo:[0,1,0] neg_hi:[0,1,0]
	v_pk_fma_f32 v[14:15], v[94:95], v[74:75], v[18:19] op_sel_hi:[1,0,1] neg_lo:[0,1,0] neg_hi:[0,1,0]
	v_add_f32_dpp v186, v178, v178 row_half_mirror row_mask:0xf bank_mask:0x5
	s_nop 1
	v_add_f32_dpp v186, v182, v182 row_half_mirror row_mask:0xf bank_mask:0xa
	v_cndmask_b32_e64 v190, v184, v186, s[98:99]
	s_waitcnt lgkmcnt(9)
	v_pk_mul_f32 v[72:73], v[12:13], v[100:101]
	v_pk_fma_f32 v[72:73], v[14:15], v[102:103], v[72:73]
	ds_read_b128 v[88:91], v2 offset:5376
	v_add_f32_e32 v74, v72, v73
	ds_read_b128 v[96:99], v2 offset:21760
	ds_read_b128 v[92:95], v2 offset:13568
	v_add_f32_dpp v74, v74, v74 quad_perm:[1,0,3,2] row_mask:0xf bank_mask:0xf bound_ctrl:1
	ds_read_b128 v[128:131], v2 offset:29952
	v_pk_fma_f32 v[16:17], v[26:27], v[108:109], v[12:13] op_sel_hi:[0,1,1]
	v_add_f32_dpp v74, v74, v74 quad_perm:[2,3,0,1] row_mask:0xf bank_mask:0xf bound_ctrl:1
	v_pk_fma_f32 v[18:19], v[26:27], v[110:111], v[14:15] op_sel_hi:[0,1,1]
	v_pk_mul_f32 v[198:199], v[12:13], v[132:133]
	v_add_f32_dpp v74, v74, v74 row_half_mirror row_mask:0xf bank_mask:0xf bound_ctrl:1
	v_pk_fma_f32 v[198:199], v[14:15], v[134:135], v[198:199]
	v_add_f32_e32 v161, v198, v199
	v_add_f32_dpp v74, v74, v74 row_mirror row_mask:0xf bank_mask:0xf bound_ctrl:1
	v_pk_fma_f32 v[12:13], v[104:105], v[74:75], v[16:17] op_sel_hi:[1,0,1] neg_lo:[0,1,0] neg_hi:[0,1,0]
	v_pk_fma_f32 v[14:15], v[106:107], v[74:75], v[18:19] op_sel_hi:[1,0,1] neg_lo:[0,1,0] neg_hi:[0,1,0]
	v_cndmask_b32_e64 v191, v186, v184, s[98:99]
	v_add_f32_dpp v183, v151, v151 row_mirror row_mask:0xf bank_mask:0x3
	s_waitcnt lgkmcnt(9)
	v_add_f32_dpp v188, v191, v190 quad_perm:[2,3,0,1] row_mask:0xf bank_mask:0xf
	v_pk_mul_f32 v[72:73], v[12:13], v[112:113]
	v_pk_fma_f32 v[72:73], v[14:15], v[114:115], v[72:73]
	ds_read_b128 v[100:103], v2 offset:5632
	v_add_f32_e32 v74, v72, v73
	ds_read_b128 v[108:111], v2 offset:22016
	ds_read_b128 v[104:107], v2 offset:13824
	v_add_f32_dpp v74, v74, v74 quad_perm:[1,0,3,2] row_mask:0xf bank_mask:0xf bound_ctrl:1
	ds_read_b128 v[132:135], v2 offset:30208
	v_pk_fma_f32 v[16:17], v[26:27], v[120:121], v[12:13] op_sel:[1,0,0] op_sel_hi:[1,1,1]
	v_add_f32_dpp v74, v74, v74 quad_perm:[2,3,0,1] row_mask:0xf bank_mask:0xf bound_ctrl:1
	v_pk_fma_f32 v[18:19], v[26:27], v[122:123], v[14:15] op_sel:[1,0,0] op_sel_hi:[1,1,1]
	v_pk_mul_f32 v[198:199], v[12:13], v[136:137]
	v_add_f32_dpp v74, v74, v74 row_half_mirror row_mask:0xf bank_mask:0xf bound_ctrl:1
	v_pk_fma_f32 v[198:199], v[14:15], v[138:139], v[198:199]
	v_add_f32_e32 v162, v198, v199
	v_add_f32_dpp v74, v74, v74 row_mirror row_mask:0xf bank_mask:0xf bound_ctrl:1
	v_pk_fma_f32 v[12:13], v[116:117], v[74:75], v[16:17] op_sel_hi:[1,0,1] neg_lo:[0,1,0] neg_hi:[0,1,0]
	v_pk_fma_f32 v[14:15], v[118:119], v[74:75], v[18:19] op_sel_hi:[1,0,1] neg_lo:[0,1,0] neg_hi:[0,1,0]
	v_add_f32_dpp v183, v159, v159 row_mirror row_mask:0xf bank_mask:0xc
	v_add_f32_dpp v187, v179, v179 row_half_mirror row_mask:0xf bank_mask:0x5
	s_waitcnt lgkmcnt(8)
	v_pk_mul_f32 v[72:73], v[12:13], v[76:77]
	v_add_f32_dpp v187, v183, v183 row_half_mirror row_mask:0xf bank_mask:0xa
	v_pk_fma_f32 v[72:73], v[14:15], v[78:79], v[72:73]
	ds_read_b128 v[112:115], v2 offset:5888
	v_add_f32_e32 v74, v72, v73
	ds_read_b128 v[120:123], v2 offset:22272
	ds_read_b128 v[116:119], v2 offset:14080
	v_add_f32_dpp v74, v74, v74 quad_perm:[1,0,3,2] row_mask:0xf bank_mask:0xf bound_ctrl:1
	ds_read_b128 v[136:139], v2 offset:30464
	v_pk_fma_f32 v[16:17], v[28:29], v[84:85], v[12:13] op_sel_hi:[0,1,1]
	v_add_f32_dpp v74, v74, v74 quad_perm:[2,3,0,1] row_mask:0xf bank_mask:0xf bound_ctrl:1
	v_pk_fma_f32 v[18:19], v[28:29], v[86:87], v[14:15] op_sel_hi:[0,1,1]
	v_pk_mul_f32 v[198:199], v[12:13], v[140:141]
	v_add_f32_dpp v74, v74, v74 row_half_mirror row_mask:0xf bank_mask:0xf bound_ctrl:1
	v_pk_fma_f32 v[198:199], v[14:15], v[142:143], v[198:199]
	v_add_f32_e32 v163, v198, v199
	v_add_f32_dpp v74, v74, v74 row_mirror row_mask:0xf bank_mask:0xf bound_ctrl:1
	v_pk_fma_f32 v[12:13], v[80:81], v[74:75], v[16:17] op_sel_hi:[1,0,1] neg_lo:[0,1,0] neg_hi:[0,1,0]
	v_pk_fma_f32 v[14:15], v[82:83], v[74:75], v[18:19] op_sel_hi:[1,0,1] neg_lo:[0,1,0] neg_hi:[0,1,0]
	v_cndmask_b32_e64 v190, v185, v187, s[98:99]
	v_cndmask_b32_e64 v191, v187, v185, s[98:99]
	s_waitcnt lgkmcnt(8)
; #define LAS __attribute__((address_space(3)))
; #define RW_LD(X, s) do { X.d = *(const LAS f32x4*)(bs + (s) * 256); X.k = *(const LAS f32x4*)(bs + 8192 + (s) * 256); X.a = *(const LAS f32x4*)(bs + 16384 + (s) * 256); \
;                          X.p = *(const LAS f32x4*)(bs + 24576 + (s) * 256); X.r = *(const LAS f32x4*)(bs + 32768 + (s) * 256); X.v = *(const LAS float*)(bv + (s) * 64); } while (0)
; #define RW_STEP(X, s) do { float sa = fmaf(S[3], X.k[3], fmaf(S[2], X.k[2], fmaf(S[1], X.k[1], S[0] * X.k[0]))); const f32x4 T = S * X.d + X.v * X.p; sa = -red16(sa); \
;                            S = T + sa * X.a; float y = fmaf(S[3], X.r[3], fmaf(S[2], X.r[2], fmaf(S[1], X.r[1], S[0] * X.r[0]))); y = red16(y); \
;                            yk = fmaf(selv[(s) & 15], y, yk); } while (0)
; #define RW_YST(s) do { if ((s) == 15) { ob[(size_t)(rowbase + c * 32 + seg) * D + 512 + h * 64 + vrow] = f2bf(yk); yk = 0.f; } } while (0)
; __device__ __forceinline__ void rwkv_scan(const Params& p, LAS unsigned char* lds, int rowbase, int T, int h, int q4, const float* S0, float* Sout) {
;     ...
;         if (comp) {
;             const LAS unsigned char* bs = b + seg * 16; const LAS unsigned char* bv = b + 40960 + vloc * 4;
;     ...
;             RwStep xa, xb, xc; float yk = 0.f;
;     ...
;             RW_LD(xa, 0); RW_LD(xb, 1);
; #pragma unroll
;             for (int s = 0; s < 30; s += 3) {
;                 RW_LD(xc, s + 2); RW_STEP(xa, s); RW_YST(s);
;                 RW_LD(xa, s + 3); RW_STEP(xb, s + 1); RW_YST(s + 1);
;                 RW_LD(xb, s + 4); RW_STEP(xc, s + 2); RW_YST(s + 2);
;             }
	v_pk_mul_f32 v[72:73], v[12:13], v[88:89]
	v_add_f32_dpp v189, v191, v190 quad_perm:[2,3,0,1] row_mask:0xf bank_mask:0xf
	v_pk_fma_f32 v[72:73], v[14:15], v[90:91], v[72:73]
	ds_read_b128 v[76:79], v2 offset:6144
	v_add_f32_e32 v74, v72, v73
	ds_read_b128 v[84:87], v2 offset:22528
	ds_read_b128 v[80:83], v2 offset:14336
	v_add_f32_dpp v74, v74, v74 quad_perm:[1,0,3,2] row_mask:0xf bank_mask:0xf bound_ctrl:1
	ds_read_b128 v[140:143], v2 offset:30720
	ds_read_b128 v[24:27], v3 offset:96
	v_add_f32_dpp v74, v74, v74 quad_perm:[2,3,0,1] row_mask:0xf bank_mask:0xf bound_ctrl:1
	v_pk_fma_f32 v[16:17], v[28:29], v[96:97], v[12:13] op_sel:[1,0,0] op_sel_hi:[1,1,1]
	v_pk_fma_f32 v[18:19], v[28:29], v[98:99], v[14:15] op_sel:[1,0,0] op_sel_hi:[1,1,1]
	v_add_f32_dpp v74, v74, v74 row_half_mirror row_mask:0xf bank_mask:0xf bound_ctrl:1
	v_pk_mul_f32 v[198:199], v[12:13], v[124:125]
	v_pk_fma_f32 v[198:199], v[14:15], v[126:127], v[198:199]
	v_add_f32_dpp v74, v74, v74 row_mirror row_mask:0xf bank_mask:0xf bound_ctrl:1
	v_add_f32_e32 v164, v198, v199
	v_pk_fma_f32 v[12:13], v[92:93], v[74:75], v[16:17] op_sel_hi:[1,0,1] neg_lo:[0,1,0] neg_hi:[0,1,0]
	v_pk_fma_f32 v[14:15], v[94:95], v[74:75], v[18:19] op_sel_hi:[1,0,1] neg_lo:[0,1,0] neg_hi:[0,1,0]
	v_cndmask_b32_e64 v190, v188, v189, s[100:101]
	v_cndmask_b32_e64 v191, v189, v188, s[100:101]
	s_waitcnt lgkmcnt(9)
	v_pk_mul_f32 v[72:73], v[12:13], v[100:101]
	v_add_f32_dpp v192, v191, v190 quad_perm:[1,0,3,2] row_mask:0xf bank_mask:0xf
	v_pk_fma_f32 v[72:73], v[14:15], v[102:103], v[72:73]
	ds_read_b128 v[88:91], v2 offset:6400
	v_add_f32_e32 v74, v72, v73
	ds_read_b128 v[96:99], v2 offset:22784
	ds_read_b128 v[92:95], v2 offset:14592
	v_add_f32_dpp v74, v74, v74 quad_perm:[1,0,3,2] row_mask:0xf bank_mask:0xf bound_ctrl:1
	ds_read_b128 v[124:127], v2 offset:30976
	v_pk_fma_f32 v[16:17], v[30:31], v[108:109], v[12:13] op_sel_hi:[0,1,1]
	v_add_f32_dpp v74, v74, v74 quad_perm:[2,3,0,1] row_mask:0xf bank_mask:0xf bound_ctrl:1
	v_pk_fma_f32 v[18:19], v[30:31], v[110:111], v[14:15] op_sel_hi:[0,1,1]
	v_pk_mul_f32 v[198:199], v[12:13], v[128:129]
	v_add_f32_dpp v74, v74, v74 row_half_mirror row_mask:0xf bank_mask:0xf bound_ctrl:1
	v_pk_fma_f32 v[198:199], v[14:15], v[130:131], v[198:199]
	v_add_f32_e32 v165, v198, v199
	v_add_f32_dpp v74, v74, v74 row_mirror row_mask:0xf bank_mask:0xf bound_ctrl:1
	v_pk_fma_f32 v[12:13], v[104:105], v[74:75], v[16:17] op_sel_hi:[1,0,1] neg_lo:[0,1,0] neg_hi:[0,1,0]
	v_pk_fma_f32 v[14:15], v[106:107], v[74:75], v[18:19] op_sel_hi:[1,0,1] neg_lo:[0,1,0] neg_hi:[0,1,0]
	v_lshlrev_b32_e32 v194, 11, v5
	v_mov_b32_e32 v195, 0
	s_waitcnt lgkmcnt(9)
	v_pk_mul_f32 v[72:73], v[12:13], v[112:113]
	v_pk_fma_f32 v[72:73], v[14:15], v[114:115], v[72:73]
	ds_read_b128 v[100:103], v2 offset:6656
	v_add_f32_e32 v74, v72, v73
	ds_read_b128 v[108:111], v2 offset:23040
	ds_read_b128 v[104:107], v2 offset:14848
	v_add_f32_dpp v74, v74, v74 quad_perm:[1,0,3,2] row_mask:0xf bank_mask:0xf bound_ctrl:1
	ds_read_b128 v[128:131], v2 offset:31232
	v_pk_fma_f32 v[16:17], v[30:31], v[120:121], v[12:13] op_sel:[1,0,0] op_sel_hi:[1,1,1]
	v_add_f32_dpp v74, v74, v74 quad_perm:[2,3,0,1] row_mask:0xf bank_mask:0xf bound_ctrl:1
	v_pk_fma_f32 v[18:19], v[30:31], v[122:123], v[14:15] op_sel:[1,0,0] op_sel_hi:[1,1,1]
	v_pk_mul_f32 v[198:199], v[12:13], v[132:133]
	v_add_f32_dpp v74, v74, v74 row_half_mirror row_mask:0xf bank_mask:0xf bound_ctrl:1
	v_pk_fma_f32 v[198:199], v[14:15], v[134:135], v[198:199]
	v_add_f32_e32 v166, v198, v199
	v_add_f32_dpp v74, v74, v74 row_mirror row_mask:0xf bank_mask:0xf bound_ctrl:1
	v_pk_fma_f32 v[12:13], v[116:117], v[74:75], v[16:17] op_sel_hi:[1,0,1] neg_lo:[0,1,0] neg_hi:[0,1,0]
	v_pk_fma_f32 v[14:15], v[118:119], v[74:75], v[18:19] op_sel_hi:[1,0,1] neg_lo:[0,1,0] neg_hi:[0,1,0]
	v_cvt_pk_bf16_f32 v193, v192, v192
	v_lshl_add_u64 v[194:195], v[6:7], 0, v[194:195]
	s_waitcnt lgkmcnt(8)
	v_pk_mul_f32 v[72:73], v[12:13], v[76:77]
	v_pk_fma_f32 v[72:73], v[14:15], v[78:79], v[72:73]
	ds_read_b128 v[112:115], v2 offset:6912
	v_add_f32_e32 v74, v72, v73
	ds_read_b128 v[120:123], v2 offset:23296
	ds_read_b128 v[116:119], v2 offset:15104
	v_add_f32_dpp v74, v74, v74 quad_perm:[1,0,3,2] row_mask:0xf bank_mask:0xf bound_ctrl:1
	ds_read_b128 v[132:135], v2 offset:31488
	v_pk_fma_f32 v[16:17], v[24:25], v[84:85], v[12:13] op_sel_hi:[0,1,1]
	v_add_f32_dpp v74, v74, v74 quad_perm:[2,3,0,1] row_mask:0xf bank_mask:0xf bound_ctrl:1
	v_pk_fma_f32 v[18:19], v[24:25], v[86:87], v[14:15] op_sel_hi:[0,1,1]
	v_pk_mul_f32 v[198:199], v[12:13], v[136:137]
	v_add_f32_dpp v74, v74, v74 row_half_mirror row_mask:0xf bank_mask:0xf bound_ctrl:1
	v_pk_fma_f32 v[198:199], v[14:15], v[138:139], v[198:199]
	v_add_f32_e32 v167, v198, v199
	v_add_f32_dpp v74, v74, v74 row_mirror row_mask:0xf bank_mask:0xf bound_ctrl:1
	v_pk_fma_f32 v[12:13], v[80:81], v[74:75], v[16:17] op_sel_hi:[1,0,1] neg_lo:[0,1,0] neg_hi:[0,1,0]
	v_pk_fma_f32 v[14:15], v[82:83], v[74:75], v[18:19] op_sel_hi:[1,0,1] neg_lo:[0,1,0] neg_hi:[0,1,0]
	global_store_short v[194:195], v193, off offset:1024
	s_waitcnt lgkmcnt(8)
; #define LAS __attribute__((address_space(3)))
; #define RW_LD(X, s) do { X.d = *(const LAS f32x4*)(bs + (s) * 256); X.k = *(const LAS f32x4*)(bs + 8192 + (s) * 256); X.a = *(const LAS f32x4*)(bs + 16384 + (s) * 256); \
;                          X.p = *(const LAS f32x4*)(bs + 24576 + (s) * 256); X.r = *(const LAS f32x4*)(bs + 32768 + (s) * 256); X.v = *(const LAS float*)(bv + (s) * 64); } while (0)
; #define RW_STEP(X, s) do { float sa = fmaf(S[3], X.k[3], fmaf(S[2], X.k[2], fmaf(S[1], X.k[1], S[0] * X.k[0]))); const f32x4 T = S * X.d + X.v * X.p; sa = -red16(sa); \
;                            S = T + sa * X.a; float y = fmaf(S[3], X.r[3], fmaf(S[2], X.r[2], fmaf(S[1], X.r[1], S[0] * X.r[0]))); y = red16(y); \
;                            yk = fmaf(selv[(s) & 15], y, yk); } while (0)
; #define RW_YST(s) do { if ((s) == 15) { ob[(size_t)(rowbase + c * 32 + seg) * D + 512 + h * 64 + vrow] = f2bf(yk); yk = 0.f; } } while (0)
; __device__ __forceinline__ void rwkv_scan(const Params& p, LAS unsigned char* lds, int rowbase, int T, int h, int q4, const float* S0, float* Sout) {
;     ...
;         if (comp) {
;             const LAS unsigned char* bs = b + seg * 16; const LAS unsigned char* bv = b + 40960 + vloc * 4;
;     ...
;             RwStep xa, xb, xc; float yk = 0.f;
;     ...
;             RW_LD(xa, 0); RW_LD(xb, 1);
; #pragma unroll
;             for (int s = 0; s < 30; s += 3) {
;                 RW_LD(xc, s + 2); RW_STEP(xa, s); RW_YST(s);
;                 RW_LD(xa, s + 3); RW_STEP(xb, s + 1); RW_YST(s + 1);
;                 RW_LD(xb, s + 4); RW_STEP(xc, s + 2); RW_YST(s + 2);
;             }
	v_pk_mul_f32 v[72:73], v[12:13], v[88:89]
	v_pk_fma_f32 v[72:73], v[14:15], v[90:91], v[72:73]
	ds_read_b128 v[76:79], v2 offset:7168
	v_add_f32_e32 v74, v72, v73
	ds_read_b128 v[84:87], v2 offset:23552
	ds_read_b128 v[80:83], v2 offset:15360
	v_add_f32_dpp v74, v74, v74 quad_perm:[1,0,3,2] row_mask:0xf bank_mask:0xf bound_ctrl:1
	ds_read_b128 v[136:139], v2 offset:31744
	ds_read_b128 v[28:31], v3 offset:112
	v_add_f32_dpp v74, v74, v74 quad_perm:[2,3,0,1] row_mask:0xf bank_mask:0xf bound_ctrl:1
	v_pk_fma_f32 v[16:17], v[24:25], v[96:97], v[12:13] op_sel:[1,0,0] op_sel_hi:[1,1,1]
	v_pk_fma_f32 v[18:19], v[24:25], v[98:99], v[14:15] op_sel:[1,0,0] op_sel_hi:[1,1,1]
	v_add_f32_dpp v74, v74, v74 row_half_mirror row_mask:0xf bank_mask:0xf bound_ctrl:1
	v_pk_mul_f32 v[198:199], v[12:13], v[140:141]
	v_pk_fma_f32 v[198:199], v[14:15], v[142:143], v[198:199]
	v_add_f32_dpp v74, v74, v74 row_mirror row_mask:0xf bank_mask:0xf bound_ctrl:1
	v_add_f32_e32 v168, v198, v199
	v_pk_fma_f32 v[12:13], v[92:93], v[74:75], v[16:17] op_sel_hi:[1,0,1] neg_lo:[0,1,0] neg_hi:[0,1,0]
	v_pk_fma_f32 v[14:15], v[94:95], v[74:75], v[18:19] op_sel_hi:[1,0,1] neg_lo:[0,1,0] neg_hi:[0,1,0]
	v_add_f32_dpp v176, v160, v160 row_mirror row_mask:0xf bank_mask:0x3
	s_waitcnt lgkmcnt(9)
	v_pk_mul_f32 v[72:73], v[12:13], v[100:101]
	v_add_f32_dpp v176, v168, v168 row_mirror row_mask:0xf bank_mask:0xc
	v_pk_fma_f32 v[72:73], v[14:15], v[102:103], v[72:73]
	ds_read_b128 v[88:91], v2 offset:7424
	v_add_f32_e32 v74, v72, v73
	ds_read_b128 v[96:99], v2 offset:23808
	ds_read_b128 v[92:95], v2 offset:15616
	v_add_f32_dpp v74, v74, v74 quad_perm:[1,0,3,2] row_mask:0xf bank_mask:0xf bound_ctrl:1
	ds_read_b128 v[140:143], v2 offset:32000
	v_pk_fma_f32 v[16:17], v[26:27], v[108:109], v[12:13] op_sel_hi:[0,1,1]
	v_add_f32_dpp v74, v74, v74 quad_perm:[2,3,0,1] row_mask:0xf bank_mask:0xf bound_ctrl:1
	v_pk_fma_f32 v[18:19], v[26:27], v[110:111], v[14:15] op_sel_hi:[0,1,1]
	v_pk_mul_f32 v[198:199], v[12:13], v[124:125]
	v_add_f32_dpp v74, v74, v74 row_half_mirror row_mask:0xf bank_mask:0xf bound_ctrl:1
	v_pk_fma_f32 v[198:199], v[14:15], v[126:127], v[198:199]
	v_add_f32_e32 v169, v198, v199
	v_add_f32_dpp v74, v74, v74 row_mirror row_mask:0xf bank_mask:0xf bound_ctrl:1
	v_pk_fma_f32 v[12:13], v[104:105], v[74:75], v[16:17] op_sel_hi:[1,0,1] neg_lo:[0,1,0] neg_hi:[0,1,0]
	v_pk_fma_f32 v[14:15], v[106:107], v[74:75], v[18:19] op_sel_hi:[1,0,1] neg_lo:[0,1,0] neg_hi:[0,1,0]
	v_add_f32_dpp v177, v161, v161 row_mirror row_mask:0xf bank_mask:0x3
	s_waitcnt lgkmcnt(9)
	v_pk_mul_f32 v[72:73], v[12:13], v[112:113]
	v_add_f32_dpp v177, v169, v169 row_mirror row_mask:0xf bank_mask:0xc
	v_pk_fma_f32 v[72:73], v[14:15], v[114:115], v[72:73]
	ds_read_b128 v[100:103], v2 offset:7680
	v_add_f32_e32 v74, v72, v73
	ds_read_b128 v[108:111], v2 offset:24064
	ds_read_b128 v[104:107], v2 offset:15872
	v_add_f32_dpp v74, v74, v74 quad_perm:[1,0,3,2] row_mask:0xf bank_mask:0xf bound_ctrl:1
	ds_read_b128 v[124:127], v2 offset:32256
	v_pk_fma_f32 v[16:17], v[26:27], v[120:121], v[12:13] op_sel:[1,0,0] op_sel_hi:[1,1,1]
	v_add_f32_dpp v74, v74, v74 quad_perm:[2,3,0,1] row_mask:0xf bank_mask:0xf bound_ctrl:1
	v_pk_fma_f32 v[18:19], v[26:27], v[122:123], v[14:15] op_sel:[1,0,0] op_sel_hi:[1,1,1]
	v_pk_mul_f32 v[198:199], v[12:13], v[128:129]
	v_add_f32_dpp v74, v74, v74 row_half_mirror row_mask:0xf bank_mask:0xf bound_ctrl:1
	v_pk_fma_f32 v[198:199], v[14:15], v[130:131], v[198:199]
	v_add_f32_e32 v170, v198, v199
	v_add_f32_dpp v74, v74, v74 row_mirror row_mask:0xf bank_mask:0xf bound_ctrl:1
	v_pk_fma_f32 v[12:13], v[116:117], v[74:75], v[16:17] op_sel_hi:[1,0,1] neg_lo:[0,1,0] neg_hi:[0,1,0]
	v_pk_fma_f32 v[14:15], v[118:119], v[74:75], v[18:19] op_sel_hi:[1,0,1] neg_lo:[0,1,0] neg_hi:[0,1,0]
	v_add_f32_dpp v178, v162, v162 row_mirror row_mask:0xf bank_mask:0x3
	s_waitcnt lgkmcnt(8)
	v_pk_mul_f32 v[72:73], v[12:13], v[76:77]
	v_add_f32_dpp v178, v170, v170 row_mirror row_mask:0xf bank_mask:0xc
	v_pk_fma_f32 v[72:73], v[14:15], v[78:79], v[72:73]
	ds_read_b128 v[112:115], v2 offset:7936
	v_add_f32_e32 v74, v72, v73
	ds_read_b128 v[120:123], v2 offset:24320
	ds_read_b128 v[116:119], v2 offset:16128
	v_add_f32_dpp v74, v74, v74 quad_perm:[1,0,3,2] row_mask:0xf bank_mask:0xf bound_ctrl:1
	ds_read_b128 v[128:131], v2 offset:32512
	v_pk_fma_f32 v[16:17], v[28:29], v[84:85], v[12:13] op_sel_hi:[0,1,1]
	v_add_f32_dpp v74, v74, v74 quad_perm:[2,3,0,1] row_mask:0xf bank_mask:0xf bound_ctrl:1
	v_pk_fma_f32 v[18:19], v[28:29], v[86:87], v[14:15] op_sel_hi:[0,1,1]
	v_pk_mul_f32 v[198:199], v[12:13], v[132:133]
	v_add_f32_dpp v74, v74, v74 row_half_mirror row_mask:0xf bank_mask:0xf bound_ctrl:1
	v_pk_fma_f32 v[198:199], v[14:15], v[134:135], v[198:199]
	v_add_f32_e32 v171, v198, v199
	v_add_f32_dpp v74, v74, v74 row_mirror row_mask:0xf bank_mask:0xf bound_ctrl:1
	v_pk_fma_f32 v[12:13], v[80:81], v[74:75], v[16:17] op_sel_hi:[1,0,1] neg_lo:[0,1,0] neg_hi:[0,1,0]
	v_pk_fma_f32 v[14:15], v[82:83], v[74:75], v[18:19] op_sel_hi:[1,0,1] neg_lo:[0,1,0] neg_hi:[0,1,0]
	v_add_f32_dpp v179, v163, v163 row_mirror row_mask:0xf bank_mask:0x3
	s_waitcnt lgkmcnt(8)
; __device__ __forceinline__ bf16_t f2bf(float f) { return (bf16_t)(cvt_pk_bf16(f, 0.f) & 0xffffu); }
; #define RW_LD(X, s) do { X.d = *(const LAS f32x4*)(bs + (s) * 256); X.k = *(const LAS f32x4*)(bs + 8192 + (s) * 256); X.a = *(const LAS f32x4*)(bs + 16384 + (s) * 256); \
;                          X.p = *(const LAS f32x4*)(bs + 24576 + (s) * 256); X.r = *(const LAS f32x4*)(bs + 32768 + (s) * 256); X.v = *(const LAS float*)(bv + (s) * 64); } while (0)
; #define RW_STEP(X, s) do { float sa = fmaf(S[3], X.k[3], fmaf(S[2], X.k[2], fmaf(S[1], X.k[1], S[0] * X.k[0]))); const f32x4 T = S * X.d + X.v * X.p; sa = -red16(sa); \
;                            S = T + sa * X.a; float y = fmaf(S[3], X.r[3], fmaf(S[2], X.r[2], fmaf(S[1], X.r[1], S[0] * X.r[0]))); y = red16(y); \
;                            yk = fmaf(selv[(s) & 15], y, yk); } while (0)
; #define RW_YST(s) do { if ((s) == 15) { ob[(size_t)(rowbase + c * 32 + seg) * D + 512 + h * 64 + vrow] = f2bf(yk); yk = 0.f; } } while (0)
; __device__ __forceinline__ void rwkv_scan(const Params& p, LAS unsigned char* lds, int rowbase, int T, int h, int q4, const float* S0, float* Sout) {
;     ...
;             for (int s = 0; s < 30; s += 3) {
;                 RW_LD(xc, s + 2); RW_STEP(xa, s); RW_YST(s);
;                 RW_LD(xa, s + 3); RW_STEP(xb, s + 1); RW_YST(s + 1);
;                 RW_LD(xb, s + 4); RW_STEP(xc, s + 2); RW_YST(s + 2);
;             }
;             RW_STEP(xa, 30); RW_STEP(xb, 31);
;             ob[(size_t)(rowbase + c * 32 + 16 + seg) * D + 512 + h * 64 + vrow] = f2bf(yk);
;     ...
;         }
;     }
;     if (comp) *(f32x4*)(Sout + vrow * 64 + seg * 4) = S;
	v_pk_mul_f32 v[72:73], v[12:13], v[88:89]
	v_add_f32_dpp v179, v171, v171 row_mirror row_mask:0xf bank_mask:0xc
	v_pk_fma_f32 v[72:73], v[14:15], v[90:91], v[72:73]
	v_pk_fma_f32 v[16:17], v[28:29], v[96:97], v[12:13] op_sel:[1,0,0] op_sel_hi:[1,1,1]
	v_add_f32_e32 v74, v72, v73
	v_pk_fma_f32 v[18:19], v[28:29], v[98:99], v[14:15] op_sel:[1,0,0] op_sel_hi:[1,1,1]
	v_pk_mul_f32 v[198:199], v[12:13], v[136:137]
	v_add_f32_dpp v74, v74, v74 quad_perm:[1,0,3,2] row_mask:0xf bank_mask:0xf bound_ctrl:1
	v_pk_fma_f32 v[198:199], v[14:15], v[138:139], v[198:199]
	v_add_f32_e32 v172, v198, v199
	v_add_f32_dpp v74, v74, v74 quad_perm:[2,3,0,1] row_mask:0xf bank_mask:0xf bound_ctrl:1
	v_add_f32_dpp v180, v164, v164 row_mirror row_mask:0xf bank_mask:0x3
	s_nop 1
	v_add_f32_dpp v180, v172, v172 row_mirror row_mask:0xf bank_mask:0xc
	v_add_f32_dpp v74, v74, v74 row_half_mirror row_mask:0xf bank_mask:0xf bound_ctrl:1
	s_nop 1
	v_add_f32_dpp v74, v74, v74 row_mirror row_mask:0xf bank_mask:0xf bound_ctrl:1
	v_pk_fma_f32 v[12:13], v[92:93], v[74:75], v[16:17] op_sel_hi:[1,0,1] neg_lo:[0,1,0] neg_hi:[0,1,0]
	v_pk_fma_f32 v[14:15], v[94:95], v[74:75], v[18:19] op_sel_hi:[1,0,1] neg_lo:[0,1,0] neg_hi:[0,1,0]
	s_waitcnt lgkmcnt(4)
	v_pk_mul_f32 v[72:73], v[12:13], v[100:101]
	v_pk_fma_f32 v[72:73], v[14:15], v[102:103], v[72:73]
	v_pk_fma_f32 v[16:17], v[30:31], v[108:109], v[12:13] op_sel_hi:[0,1,1]
	v_add_f32_e32 v74, v72, v73
	v_pk_fma_f32 v[18:19], v[30:31], v[110:111], v[14:15] op_sel_hi:[0,1,1]
	v_pk_mul_f32 v[198:199], v[12:13], v[140:141]
	v_add_f32_dpp v74, v74, v74 quad_perm:[1,0,3,2] row_mask:0xf bank_mask:0xf bound_ctrl:1
	v_pk_fma_f32 v[198:199], v[14:15], v[142:143], v[198:199]
	v_add_f32_e32 v173, v198, v199
	v_add_f32_dpp v74, v74, v74 quad_perm:[2,3,0,1] row_mask:0xf bank_mask:0xf bound_ctrl:1
	v_add_f32_dpp v184, v176, v176 row_half_mirror row_mask:0xf bank_mask:0x5
	s_nop 1
	v_add_f32_dpp v184, v180, v180 row_half_mirror row_mask:0xf bank_mask:0xa
	v_add_f32_dpp v74, v74, v74 row_half_mirror row_mask:0xf bank_mask:0xf bound_ctrl:1
	s_nop 1
	v_add_f32_dpp v74, v74, v74 row_mirror row_mask:0xf bank_mask:0xf bound_ctrl:1
	v_pk_fma_f32 v[12:13], v[104:105], v[74:75], v[16:17] op_sel_hi:[1,0,1] neg_lo:[0,1,0] neg_hi:[0,1,0]
	v_pk_fma_f32 v[14:15], v[106:107], v[74:75], v[18:19] op_sel_hi:[1,0,1] neg_lo:[0,1,0] neg_hi:[0,1,0]
	s_waitcnt lgkmcnt(0)
	v_pk_mul_f32 v[72:73], v[12:13], v[112:113]
	v_pk_fma_f32 v[72:73], v[14:15], v[114:115], v[72:73]
	v_pk_fma_f32 v[16:17], v[30:31], v[120:121], v[12:13] op_sel:[1,0,0] op_sel_hi:[1,1,1]
	v_add_f32_e32 v74, v72, v73
	v_pk_fma_f32 v[18:19], v[30:31], v[122:123], v[14:15] op_sel:[1,0,0] op_sel_hi:[1,1,1]
	v_pk_mul_f32 v[198:199], v[12:13], v[124:125]
	v_add_f32_dpp v74, v74, v74 quad_perm:[1,0,3,2] row_mask:0xf bank_mask:0xf bound_ctrl:1
	v_pk_fma_f32 v[198:199], v[14:15], v[126:127], v[198:199]
	v_add_f32_e32 v174, v198, v199
	v_add_f32_dpp v74, v74, v74 quad_perm:[2,3,0,1] row_mask:0xf bank_mask:0xf bound_ctrl:1
	v_add_f32_dpp v181, v165, v165 row_mirror row_mask:0xf bank_mask:0x3
	s_nop 0
	v_add_f32_dpp v74, v74, v74 row_half_mirror row_mask:0xf bank_mask:0xf bound_ctrl:1
	v_add_f32_dpp v185, v177, v177 row_half_mirror row_mask:0xf bank_mask:0x5
	v_add_f32_dpp v181, v173, v173 row_mirror row_mask:0xf bank_mask:0xc
	v_add_f32_dpp v74, v74, v74 row_mirror row_mask:0xf bank_mask:0xf bound_ctrl:1
	v_pk_fma_f32 v[12:13], v[116:117], v[74:75], v[16:17] op_sel_hi:[1,0,1] neg_lo:[0,1,0] neg_hi:[0,1,0]
	v_pk_fma_f32 v[14:15], v[118:119], v[74:75], v[18:19] op_sel_hi:[1,0,1] neg_lo:[0,1,0] neg_hi:[0,1,0]
	ds_read_b128 v[20:23], v4
	v_pk_mul_f32 v[198:199], v[12:13], v[128:129]
	v_pk_fma_f32 v[198:199], v[14:15], v[130:131], v[198:199]
	v_add_f32_e32 v175, v198, v199
	v_add_f32_dpp v185, v181, v181 row_half_mirror row_mask:0xf bank_mask:0xa
	v_add_f32_dpp v182, v166, v166 row_mirror row_mask:0xf bank_mask:0x3
	s_nop 1
	v_add_f32_dpp v182, v174, v174 row_mirror row_mask:0xf bank_mask:0xc
	v_add_f32_dpp v186, v178, v178 row_half_mirror row_mask:0xf bank_mask:0x5
	s_nop 1
	v_add_f32_dpp v186, v182, v182 row_half_mirror row_mask:0xf bank_mask:0xa
	v_cndmask_b32_e64 v190, v184, v186, s[98:99]
	v_cndmask_b32_e64 v191, v186, v184, s[98:99]
	s_nop 1
	v_add_f32_dpp v188, v191, v190 quad_perm:[2,3,0,1] row_mask:0xf bank_mask:0xf
	v_add_f32_dpp v183, v167, v167 row_mirror row_mask:0xf bank_mask:0x3
	s_nop 1
	v_add_f32_dpp v183, v175, v175 row_mirror row_mask:0xf bank_mask:0xc
	v_add_f32_dpp v187, v179, v179 row_half_mirror row_mask:0xf bank_mask:0x5
	s_waitcnt lgkmcnt(0)
	v_pk_mul_f32 v[12:13], v[12:13], v[20:21]
	v_add_f32_dpp v187, v183, v183 row_half_mirror row_mask:0xf bank_mask:0xa
	v_pk_mul_f32 v[14:15], v[14:15], v[22:23]
	v_cndmask_b32_e64 v190, v185, v187, s[98:99]
	v_cndmask_b32_e64 v191, v187, v185, s[98:99]
	s_nop 1
	v_add_f32_dpp v189, v191, v190 quad_perm:[2,3,0,1] row_mask:0xf bank_mask:0xf
	v_cndmask_b32_e64 v190, v188, v189, s[100:101]
	v_cndmask_b32_e64 v191, v189, v188, s[100:101]
	v_add_u32_e32 v196, 16, v5
	v_lshlrev_b32_e32 v194, 11, v196
	v_add_f32_dpp v192, v191, v190 quad_perm:[1,0,3,2] row_mask:0xf bank_mask:0xf
	v_mov_b32_e32 v195, 0
	v_cvt_pk_bf16_f32 v193, v192, v192
	v_lshl_add_u64 v[194:195], v[6:7], 0, v[194:195]
	global_store_short v[194:195], v193, off offset:1024
	v_add_u32_e32 v5, 32, v5
	s_bitcmp1_b32 s22, 0
	s_cselect_b32 s4, s39, s38
	v_add_u32_e32 v2, s4, v2
	v_add_u32_e32 v3, s4, v3
	v_add_u32_e32 v4, s4, v4
	s_add_i32 s22, s22, 1
	s_cmpk_lt_i32 s22, 128
	s_waitcnt lgkmcnt(0)
	s_cbranch_scc1 .Lrw3_cloop
	global_store_dwordx4 v[8:9], v[12:15], off
	s_branch .LBB0_738
